# v7 + deferred weight copies split 75/25 between odd and even XCD groups (was 100/0): half the stagger between the two chip halves
# speedup vs baseline: 1.0034x; 1.0034x over previous
; __device__ __forceinline__ int item_b(int i) {
;     if (i < I_AB1) return O_AB1 + I_AB1 + i; i -= I_AB1;
;     if (i < 2 * I_C1) return O_C1 + i; i -= 2 * I_C1;
;     if (i < I_2) return O_AB2 + I_2 + i; i -= I_2;
;     if (i < 2 * I_2) return O_C2 + i; i -= 2 * I_2;
; __device__ __forceinline__ void p0_weights(Frame& F0, int part, int gw, int NGW, int half = -1) {
;     ...
;     constexpr int NB_ODD = (int)((long)p0seg::NB * PB_ODD_PCT / 100);
;     const int base = (part == 1 && half == 0) ? NB_ODD : 0;
;     const int n = part == 0 ? p0seg::NA : (part == 1 ? (half == 1 ? NB_ODD : (half == 0 ? p0seg::NB - NB_ODD : p0seg::NB)) : p0seg::NITEMS);
;     ...
;     if (gw < n) {
.LBB0_454:
	v_readlane_b32 s13, v254, 0
	s_and_b32 s20, s13, 1
	s_bfe_i32 s10, s13, 0x10000
	s_cmp_eq_u32 s20, 0
	s_cselect_b64 s[4:5], -1, 0
	s_lshl_b32 s6, s13, 2
	s_and_b32 s6, s6, -8
	v_readlane_b32 s21, v254, 9
	s_add_i32 s26, s21, s6
	s_and_b32 s28, s10, 0x2140
	s_add_i32 s28, s28, 0x10a0
	s_waitcnt vmcnt(0)
	v_mbcnt_lo_u32_b32 v4, -1, 0
	v_mbcnt_hi_u32_b32 v4, -1, v4
	s_mov_b64 s[8:9], s[70:71]
	s_mov_b64 s[16:17], s[72:73]
	s_load_dword s11, s[72:73], 0xe0
	s_mov_b32 s12, s13
	s_mov_b64 s[6:7], s[68:69]
	s_cmp_ge_i32 s26, s28
	s_waitcnt lgkmcnt(0)
	s_cbranch_scc1 .LBB0_630
	s_and_b64 s[4:5], s[4:5], exec
	s_cselect_b32 s49, 0x31e0, 0
	s_add_i32 s4, s26, s49
	s_cmpk_lt_i32 s4, 0x2a00
	s_movk_i32 s5, 0xa00
	s_cbranch_scc1 .LBB0_457
	s_cmpk_lt_u32 s4, 0x4200
	s_movk_i32 s5, 0x2200
	s_cselect_b32 s5, s5, 0x2280
	s_cmpk_gt_u32 s4, 0x3bff
	s_cselect_b32 s5, s5, 0x1000
	s_cmpk_gt_u32 s4, 0x35ff
	s_cselect_b32 s5, s5, 0xe00
